# C1 with the four GEMM K-loop heads aligned to 64 bytes
# baseline (speedup 1.0000x reference)
; #define PG8_LAS __attribute__((address_space(3)))
; template <class Epi, class Sched, bool ALIGN_EPI = false, bool SP2 = false, bool ABLK = false, bool BBLK = false>
; __device__ __forceinline__ void gemm_phase(PG8_LAS unsigned char* lds, const Gemm g, const Sched& S, const Epi& E) {
;     ...
;         const bool has_next = S.next(ui + 1, nxt);
;         PG8_LAS unsigned char* const rs_area = lds + STAGE_BYTES + wid * 512;
;         E.stage(cur, rs_area, wr, lane);
;         const char* nA = has_next ? (const char*)g.A + (size_t)nxt.pm * tstep : cA; const char* nB = has_next ? (const char*)g.Bt + (size_t)nxt.pn * tstep : cB;
;         for (int t = 0; t < nt; t += 2) {
;             const bool last = (t == nt - 2);
;             const char* a1 = cA + (size_t)(t + 1) * kstepA;
;             const char* a2 = last ? nA : cA + (size_t)(t + 2) * kstepA; const char* b2 = last ? nB : cB + (size_t)(t + 2) * kstepB;
;             const char* a3 = a2 + kstepA; const char* b3 = b2 + kstepB;
;     ...
; #pragma unroll
;         for (int a = 0; a < 2; ++a)
; #pragma unroll
;             for (int b = 0; b < 2; ++b)
; #pragma unroll
;                 for (int m = 0; m < 4; ++m)
; #pragma unroll
;                     for (int n = 0; n < 2; ++n) acc[a][b][m][n] = (f32x4){0.f, 0.f, 0.f, 0.f};
;         cur = nxt; cA = nA; cB = nB; ++ui;
.LBB0_184:
	s_lshl_b32 s10, s18, 8
	s_ashr_i32 s11, s10, 31
	s_mov_b32 m0, s64
	v_lshl_add_u64 v[4:5], s[10:11], 2, v[144:145]
	global_load_lds_dword v[4:5], off
	v_lshl_add_u64 v[4:5], v[4:5], 0, s[90:91]
	s_add_i32 m0, s64, 0x100
	s_ashr_i32 s9, s8, 31
	global_load_lds_dword v[4:5], off
	s_lshl_b64 s[10:11], s[8:9], 20
	v_readlane_b32 s16, v252, 27
	v_readlane_b32 s17, v252, 28
	s_add_u32 s10, s16, s10
	s_addc_u32 s11, s17, s11
	s_and_b64 s[16:17], s[2:3], exec
	s_cselect_b32 s9, s11, s21
	s_cselect_b32 s70, s10, s20
	s_ashr_i32 s7, s6, 31
	s_lshl_b64 s[16:17], s[6:7], 20
	s_add_u32 s16, s29, s16
	s_addc_u32 s17, s30, s17
	s_and_b64 s[24:25], s[2:3], exec
	s_cselect_b32 s7, s17, s23
	s_cselect_b32 s71, s16, s22
	s_add_u32 s20, s20, 0xc000
	s_addc_u32 s21, s21, 0
	s_add_u32 s77, s22, 0x10000
	v_mov_b32_e32 v4, 0
	s_addc_u32 vcc_lo, s23, 0
	s_mov_b32 vcc_hi, -2
	v_mov_b32_e32 v5, v4
	v_mov_b64_e32 v[6:7], 0
	v_mov_b64_e32 v[8:9], 0
	v_mov_b64_e32 v[10:11], 0
	v_mov_b64_e32 v[20:21], 0
	v_mov_b64_e32 v[22:23], 0
	v_mov_b64_e32 v[24:25], 0
	v_mov_b64_e32 v[26:27], 0
	v_mov_b64_e32 v[40:41], 0
	v_mov_b64_e32 v[42:43], 0
	v_mov_b64_e32 v[44:45], 0
	v_mov_b64_e32 v[46:47], 0
	v_mov_b64_e32 v[56:57], 0
	v_mov_b64_e32 v[58:59], 0
	v_mov_b64_e32 v[60:61], 0
	v_mov_b64_e32 v[62:63], 0
	v_mov_b64_e32 v[12:13], 0
	v_mov_b64_e32 v[14:15], 0
	v_mov_b64_e32 v[16:17], 0
	v_mov_b64_e32 v[18:19], 0
	v_mov_b64_e32 v[28:29], 0
	v_mov_b64_e32 v[30:31], 0
	v_mov_b64_e32 v[32:33], 0
	v_mov_b64_e32 v[34:35], 0
	v_mov_b64_e32 v[48:49], 0
	v_mov_b64_e32 v[50:51], 0
	v_mov_b64_e32 v[52:53], 0
	v_mov_b64_e32 v[54:55], 0
	v_mov_b64_e32 v[64:65], 0
	v_mov_b64_e32 v[66:67], 0
	v_mov_b64_e32 v[68:69], 0
	v_mov_b64_e32 v[70:71], 0
	v_mov_b64_e32 v[72:73], 0
	v_mov_b64_e32 v[74:75], 0
	v_mov_b64_e32 v[76:77], 0
	v_mov_b64_e32 v[78:79], 0
	v_mov_b64_e32 v[88:89], 0
	v_mov_b64_e32 v[90:91], 0
	v_mov_b64_e32 v[92:93], 0
	v_mov_b64_e32 v[94:95], 0
	v_mov_b64_e32 v[104:105], 0
	v_mov_b64_e32 v[106:107], 0
	v_mov_b64_e32 v[108:109], 0
	v_mov_b64_e32 v[110:111], 0
	v_mov_b64_e32 v[120:121], 0
	v_mov_b64_e32 v[122:123], 0
	v_mov_b64_e32 v[124:125], 0
	v_mov_b64_e32 v[126:127], 0
	v_mov_b64_e32 v[80:81], 0
	v_mov_b64_e32 v[82:83], 0
	v_mov_b64_e32 v[84:85], 0
	v_mov_b64_e32 v[86:87], 0
	v_mov_b64_e32 v[96:97], 0
	v_mov_b64_e32 v[98:99], 0
	v_mov_b64_e32 v[100:101], 0
	v_mov_b64_e32 v[102:103], 0
	v_mov_b64_e32 v[112:113], 0
	v_mov_b64_e32 v[114:115], 0
	v_mov_b64_e32 v[116:117], 0
	v_mov_b64_e32 v[118:119], 0
	v_mov_b64_e32 v[128:129], 0
	v_mov_b64_e32 v[130:131], 0
	v_mov_b64_e32 v[132:133], 0
	v_mov_b64_e32 v[134:135], 0
	.p2align	6

; template <class Epi, class Sched, bool ALIGN_EPI = false, bool SP2 = false, bool ABLK = false, bool BBLK = false>
; __device__ __forceinline__ void gemm_phase(PG8_LAS unsigned char* lds, const Gemm g, const Sched& S, const Epi& E) {
;     ...
;         const char* nA = has_next ? (const char*)g.A + (size_t)nxt.pm * tstep : cA; const char* nB = has_next ? (const char*)g.Bt + (size_t)nxt.pn * tstep : cB;
;         for (int t = 0; t < nt; t += 2) {
;             const bool last = (t == nt - 2);
;             const char* a1 = cA + (size_t)(t + 1) * kstepA;
;             const char* a2 = last ? nA : cA + (size_t)(t + 2) * kstepA; const char* b2 = last ? nB : cB + (size_t)(t + 2) * kstepB;
;             const char* a3 = a2 + kstepA; const char* b3 = b2 + kstepB;
;     ...
; #pragma unroll
;         for (int a = 0; a < 2; ++a)
; #pragma unroll
;             for (int b = 0; b < 2; ++b)
; #pragma unroll
;                 for (int m = 0; m < 4; ++m)
; #pragma unroll
;                     for (int n = 0; n < 2; ++n) acc[a][b][m][n] = (f32x4){0.f, 0.f, 0.f, 0.f};
;         cur = nxt; cA = nA; cB = nB; ++ui;
.LBB0_438:
	s_add_u32 s10, s10, 0xc000
	s_addc_u32 s11, s11, 0
	s_add_u32 vcc_lo, s16, 0x10000
	v_mov_b32_e32 v4, 0
	s_addc_u32 vcc_hi, s17, 0
	s_mov_b32 s13, -2
	v_mov_b32_e32 v5, v4
	v_mov_b64_e32 v[6:7], 0
	v_mov_b64_e32 v[8:9], 0
	v_mov_b64_e32 v[10:11], 0
	v_mov_b64_e32 v[12:13], 0
	v_mov_b64_e32 v[14:15], 0
	v_mov_b64_e32 v[16:17], 0
	v_mov_b64_e32 v[18:19], 0
	v_mov_b64_e32 v[28:29], 0
	v_mov_b64_e32 v[30:31], 0
	v_mov_b64_e32 v[32:33], 0
	v_mov_b64_e32 v[34:35], 0
	v_mov_b64_e32 v[48:49], 0
	v_mov_b64_e32 v[50:51], 0
	v_mov_b64_e32 v[52:53], 0
	v_mov_b64_e32 v[54:55], 0
	v_mov_b64_e32 v[20:21], 0
	v_mov_b64_e32 v[22:23], 0
	v_mov_b64_e32 v[24:25], 0
	v_mov_b64_e32 v[26:27], 0
	v_mov_b64_e32 v[40:41], 0
	v_mov_b64_e32 v[42:43], 0
	v_mov_b64_e32 v[44:45], 0
	v_mov_b64_e32 v[46:47], 0
	v_mov_b64_e32 v[56:57], 0
	v_mov_b64_e32 v[58:59], 0
	v_mov_b64_e32 v[60:61], 0
	v_mov_b64_e32 v[62:63], 0
	v_mov_b64_e32 v[64:65], 0
	v_mov_b64_e32 v[66:67], 0
	v_mov_b64_e32 v[68:69], 0
	v_mov_b64_e32 v[70:71], 0
	v_mov_b64_e32 v[72:73], 0
	v_mov_b64_e32 v[74:75], 0
	v_mov_b64_e32 v[76:77], 0
	v_mov_b64_e32 v[78:79], 0
	v_mov_b64_e32 v[80:81], 0
	v_mov_b64_e32 v[82:83], 0
	v_mov_b64_e32 v[84:85], 0
	v_mov_b64_e32 v[86:87], 0
	v_mov_b64_e32 v[96:97], 0
	v_mov_b64_e32 v[98:99], 0
	v_mov_b64_e32 v[100:101], 0
	v_mov_b64_e32 v[102:103], 0
	v_mov_b64_e32 v[112:113], 0
	v_mov_b64_e32 v[114:115], 0
	v_mov_b64_e32 v[116:117], 0
	v_mov_b64_e32 v[118:119], 0
	v_mov_b64_e32 v[88:89], 0
	v_mov_b64_e32 v[90:91], 0
	v_mov_b64_e32 v[92:93], 0
	v_mov_b64_e32 v[94:95], 0
	v_mov_b64_e32 v[104:105], 0
	v_mov_b64_e32 v[106:107], 0
	v_mov_b64_e32 v[108:109], 0
	v_mov_b64_e32 v[110:111], 0
	v_mov_b64_e32 v[120:121], 0
	v_mov_b64_e32 v[122:123], 0
	v_mov_b64_e32 v[124:125], 0
	v_mov_b64_e32 v[126:127], 0
	v_mov_b64_e32 v[128:129], 0
	v_mov_b64_e32 v[130:131], 0
	v_mov_b64_e32 v[132:133], 0
	v_mov_b64_e32 v[134:135], 0
	.p2align	6

; #define PG8_LAS __attribute__((address_space(3)))
; template <class Epi, class Sched, bool ALIGN_EPI = false, bool SP2 = false, bool ABLK = false, bool BBLK = false>
; __device__ __forceinline__ void gemm_phase(PG8_LAS unsigned char* lds, const Gemm g, const Sched& S, const Epi& E) {
;     ...
;         const bool has_next = S.next(ui + 1, nxt);
;         PG8_LAS unsigned char* const rs_area = lds + STAGE_BYTES + wid * 512;
;         E.stage(cur, rs_area, wr, lane);
;         const char* nA = has_next ? (const char*)g.A + (size_t)nxt.pm * tstep : cA; const char* nB = has_next ? (const char*)g.Bt + (size_t)nxt.pn * tstep : cB;
;         for (int t = 0; t < nt; t += 2) {
;             const bool last = (t == nt - 2);
;             const char* a1 = cA + (size_t)(t + 1) * kstepA;
;             const char* a2 = last ? nA : cA + (size_t)(t + 2) * kstepA; const char* b2 = last ? nB : cB + (size_t)(t + 2) * kstepB;
;             const char* a3 = a2 + kstepA; const char* b3 = b2 + kstepB;
;     ...
; #pragma unroll
;         for (int a = 0; a < 2; ++a)
; #pragma unroll
;             for (int b = 0; b < 2; ++b)
; #pragma unroll
;                 for (int m = 0; m < 4; ++m)
; #pragma unroll
;                     for (int n = 0; n < 2; ++n) acc[a][b][m][n] = (f32x4){0.f, 0.f, 0.f, 0.f};
;         cur = nxt; cA = nA; cB = nB; ++ui;
.LBB0_915:
	s_lshl_b32 s18, s0, 8
	s_ashr_i32 s19, s18, 31
	s_mov_b32 m0, s63
	v_lshl_add_u64 v[4:5], s[18:19], 2, v[144:145]
	v_lshl_add_u64 v[6:7], v[4:5], 0, s[90:91]
	global_load_lds_dword v[4:5], off
	s_add_i32 m0, s63, 0x100
	s_mov_b32 s0, s1
	global_load_lds_dword v[6:7], off
	s_ashr_i32 s1, s1, 31
	s_lshl_b64 s[10:11], s[0:1], 20
	v_readlane_b32 s16, v252, 27
	v_readlane_b32 s17, v252, 28
	s_add_u32 s10, s16, s10
	s_addc_u32 s11, s17, s11
	s_and_b64 s[16:17], s[2:3], exec
	s_cselect_b32 s1, s11, s21
	s_cselect_b32 s19, s10, s20
	s_ashr_i32 s9, s8, 31
	s_lshl_b64 s[16:17], s[8:9], 20
	v_readlane_b32 s24, v254, 5
	v_readlane_b32 s25, v254, 6
	s_add_u32 s16, s24, s16
	s_addc_u32 s17, s25, s17
	s_and_b64 s[24:25], s[2:3], exec
	s_cselect_b32 s9, s17, s23
	s_cselect_b32 s65, s16, s22
	s_add_u32 s20, s20, 0xc000
	s_addc_u32 s21, s21, 0
	s_add_u32 s70, s22, 0x10000
	v_mov_b32_e32 v4, 0
	s_addc_u32 s71, s23, 0
	s_mov_b32 s13, -2
	v_mov_b32_e32 v5, v4
	v_mov_b64_e32 v[6:7], 0
	v_mov_b64_e32 v[8:9], 0
	v_mov_b64_e32 v[10:11], 0
	v_mov_b64_e32 v[12:13], 0
	v_mov_b64_e32 v[14:15], 0
	v_mov_b64_e32 v[20:21], 0
	v_mov_b64_e32 v[22:23], 0
	v_mov_b64_e32 v[28:29], 0
	v_mov_b64_e32 v[30:31], 0
	v_mov_b64_e32 v[40:41], 0
	v_mov_b64_e32 v[42:43], 0
	v_mov_b64_e32 v[48:49], 0
	v_mov_b64_e32 v[50:51], 0
	v_mov_b64_e32 v[56:57], 0
	v_mov_b64_e32 v[58:59], 0
	v_mov_b64_e32 v[16:17], 0
	v_mov_b64_e32 v[18:19], 0
	v_mov_b64_e32 v[24:25], 0
	v_mov_b64_e32 v[26:27], 0
	v_mov_b64_e32 v[32:33], 0
	v_mov_b64_e32 v[34:35], 0
	v_mov_b64_e32 v[44:45], 0
	v_mov_b64_e32 v[46:47], 0
	v_mov_b64_e32 v[52:53], 0
	v_mov_b64_e32 v[54:55], 0
	v_mov_b64_e32 v[60:61], 0
	v_mov_b64_e32 v[62:63], 0
	v_mov_b64_e32 v[64:65], 0
	v_mov_b64_e32 v[66:67], 0
	v_mov_b64_e32 v[68:69], 0
	v_mov_b64_e32 v[70:71], 0
	v_mov_b64_e32 v[72:73], 0
	v_mov_b64_e32 v[74:75], 0
	v_mov_b64_e32 v[76:77], 0
	v_mov_b64_e32 v[78:79], 0
	v_mov_b64_e32 v[80:81], 0
	v_mov_b64_e32 v[82:83], 0
	v_mov_b64_e32 v[88:89], 0
	v_mov_b64_e32 v[90:91], 0
	v_mov_b64_e32 v[96:97], 0
	v_mov_b64_e32 v[98:99], 0
	v_mov_b64_e32 v[104:105], 0
	v_mov_b64_e32 v[106:107], 0
	v_mov_b64_e32 v[112:113], 0
	v_mov_b64_e32 v[114:115], 0
	v_mov_b64_e32 v[120:121], 0
	v_mov_b64_e32 v[122:123], 0
	v_mov_b64_e32 v[84:85], 0
	v_mov_b64_e32 v[86:87], 0
	v_mov_b64_e32 v[92:93], 0
	v_mov_b64_e32 v[94:95], 0
	v_mov_b64_e32 v[100:101], 0
	v_mov_b64_e32 v[102:103], 0
	v_mov_b64_e32 v[108:109], 0
	v_mov_b64_e32 v[110:111], 0
	v_mov_b64_e32 v[116:117], 0
	v_mov_b64_e32 v[118:119], 0
	v_mov_b64_e32 v[124:125], 0
	v_mov_b64_e32 v[126:127], 0
	v_mov_b64_e32 v[128:129], 0
	v_mov_b64_e32 v[130:131], 0
	v_mov_b64_e32 v[132:133], 0
	v_mov_b64_e32 v[134:135], 0
	.p2align	6

; template <class Epi, class Sched, bool ALIGN_EPI = false, bool SP2 = false, bool ABLK = false, bool BBLK = false>
; __device__ __forceinline__ void gemm_phase(PG8_LAS unsigned char* lds, const Gemm g, const Sched& S, const Epi& E) {
;     ...
;         const char* nA = has_next ? (const char*)g.A + (size_t)nxt.pm * tstep : cA; const char* nB = has_next ? (const char*)g.Bt + (size_t)nxt.pn * tstep : cB;
;         for (int t = 0; t < nt; t += 2) {
;             const bool last = (t == nt - 2);
;             const char* a1 = cA + (size_t)(t + 1) * kstepA;
;             const char* a2 = last ? nA : cA + (size_t)(t + 2) * kstepA; const char* b2 = last ? nB : cB + (size_t)(t + 2) * kstepB;
;             const char* a3 = a2 + kstepA; const char* b3 = b2 + kstepB;
;     ...
; #pragma unroll
;         for (int a = 0; a < 2; ++a)
; #pragma unroll
;             for (int b = 0; b < 2; ++b)
; #pragma unroll
;                 for (int m = 0; m < 4; ++m)
; #pragma unroll
;                     for (int n = 0; n < 2; ++n) acc[a][b][m][n] = (f32x4){0.f, 0.f, 0.f, 0.f};
;         cur = nxt; cA = nA; cB = nB; ++ui;
.LBB0_2110:
	s_ashr_i32 s17, s16, 31
	s_lshl_b64 s[12:13], s[16:17], 20
	s_add_u32 s18, s72, s12
	s_addc_u32 s19, s73, s13
	s_and_b64 s[12:13], s[4:5], exec
	s_cselect_b32 s12, s19, s23
	s_cselect_b32 s17, s18, s22
	s_ashr_i32 s11, s10, 31
	s_lshl_b64 s[20:21], s[10:11], 20
	v_readlane_b32 s26, v254, 3
	v_readlane_b32 s27, v254, 4
	s_add_u32 s20, s26, s20
	s_addc_u32 s21, s27, s21
	s_and_b64 s[26:27], s[4:5], exec
	s_cselect_b32 s11, s21, s25
	s_cselect_b32 s77, s20, s24
	s_add_u32 s22, s22, 0xc000
	s_addc_u32 s23, s23, 0
	s_add_u32 s82, s24, 0x10000
	v_mov_b32_e32 v4, 0
	s_addc_u32 vcc_lo, s25, 0
	s_mov_b32 s13, -2
	v_mov_b32_e32 v5, v4
	v_mov_b64_e32 v[6:7], 0
	v_mov_b64_e32 v[8:9], 0
	v_mov_b64_e32 v[10:11], 0
	v_mov_b64_e32 v[12:13], 0
	v_mov_b64_e32 v[14:15], 0
	v_mov_b64_e32 v[16:17], 0
	v_mov_b64_e32 v[18:19], 0
	v_mov_b64_e32 v[28:29], 0
	v_mov_b64_e32 v[30:31], 0
	v_mov_b64_e32 v[32:33], 0
	v_mov_b64_e32 v[34:35], 0
	v_mov_b64_e32 v[48:49], 0
	v_mov_b64_e32 v[50:51], 0
	v_mov_b64_e32 v[52:53], 0
	v_mov_b64_e32 v[54:55], 0
	v_mov_b64_e32 v[20:21], 0
	v_mov_b64_e32 v[22:23], 0
	v_mov_b64_e32 v[24:25], 0
	v_mov_b64_e32 v[26:27], 0
	v_mov_b64_e32 v[40:41], 0
	v_mov_b64_e32 v[42:43], 0
	v_mov_b64_e32 v[44:45], 0
	v_mov_b64_e32 v[46:47], 0
	v_mov_b64_e32 v[56:57], 0
	v_mov_b64_e32 v[58:59], 0
	v_mov_b64_e32 v[60:61], 0
	v_mov_b64_e32 v[62:63], 0
	v_mov_b64_e32 v[64:65], 0
	v_mov_b64_e32 v[66:67], 0
	v_mov_b64_e32 v[68:69], 0
	v_mov_b64_e32 v[70:71], 0
	v_mov_b64_e32 v[72:73], 0
	v_mov_b64_e32 v[74:75], 0
	v_mov_b64_e32 v[76:77], 0
	v_mov_b64_e32 v[78:79], 0
	v_mov_b64_e32 v[80:81], 0
	v_mov_b64_e32 v[82:83], 0
	v_mov_b64_e32 v[84:85], 0
	v_mov_b64_e32 v[86:87], 0
	v_mov_b64_e32 v[96:97], 0
	v_mov_b64_e32 v[98:99], 0
	v_mov_b64_e32 v[100:101], 0
	v_mov_b64_e32 v[102:103], 0
	v_mov_b64_e32 v[112:113], 0
	v_mov_b64_e32 v[114:115], 0
	v_mov_b64_e32 v[116:117], 0
	v_mov_b64_e32 v[118:119], 0
	v_mov_b64_e32 v[88:89], 0
	v_mov_b64_e32 v[90:91], 0
	v_mov_b64_e32 v[92:93], 0
	v_mov_b64_e32 v[94:95], 0
	v_mov_b64_e32 v[104:105], 0
	v_mov_b64_e32 v[106:107], 0
	v_mov_b64_e32 v[108:109], 0
	v_mov_b64_e32 v[110:111], 0
	v_mov_b64_e32 v[120:121], 0
	v_mov_b64_e32 v[122:123], 0
	v_mov_b64_e32 v[124:125], 0
	v_mov_b64_e32 v[126:127], 0
	v_mov_b64_e32 v[128:129], 0
	v_mov_b64_e32 v[130:131], 0
	v_mov_b64_e32 v[132:133], 0
	v_mov_b64_e32 v[134:135], 0
	.p2align	6
